# attention QK: last two MFMAs issued back-to-back ahead of the row-max VALU chain (dense MFMA issue), on top of interleaved K/V reads and hoisted invariants
# speedup vs baseline: 1.0394x; 1.0017x over previous
; #define MAX3(a, b, c) ({ float r_; asm("v_max3_f32 %0, %1, %2, %3" : "=v"(r_) : "v"(a), "v"(b), "v"(c)); r_; })
; __device__ __forceinline__ void unit(LAS unsigned char* lds, const bf16* __restrict__ Q, const bf16* __restrict__ Kn, const bf16* __restrict__ Kr, const bf16* __restrict__ Vt, bf16* __restrict__ O,
;                                      int tokbase, int S, int h, int qb, const int tid) {
;     ...
;             for (int d0 = 0; d0 < 6; ++d0) { p0 = __builtin_amdgcn_mfma_f32_32x32x16_bf16(kf0[d0], qf[d0], p0, 0, 0, 0); p1 = __builtin_amdgcn_mfma_f32_32x32x16_bf16(kf1[d0], qf[d0], p1, 0, 0, 0); }
;         }
;         float mx = MAX3(p0[0], p0[1], p0[2]);
;         mx = MAX3(mx, p0[3], p0[4]); mx = MAX3(mx, p0[5], p0[6]); mx = MAX3(mx, p0[7], p0[8]); mx = MAX3(mx, p0[9], p0[10]); mx = MAX3(mx, p0[11], p0[12]);
;         mx = MAX3(mx, p0[13], p0[14]); mx = MAX3(mx, p0[15], p1[0]); mx = MAX3(mx, p1[1], p1[2]); mx = MAX3(mx, p1[3], p1[4]); mx = MAX3(mx, p1[5], p1[6]);
;         mx = MAX3(mx, p1[7], p1[8]); mx = MAX3(mx, p1[9], p1[10]); mx = MAX3(mx, p1[11], p1[12]); mx = MAX3(mx, p1[13], p1[14]); mx = MAX3(mx, p1[15], p1[15]);
.LBB0_729:
	s_or_b64 exec, exec, s[26:27]
	global_load_dwordx4 v[126:129], v[162:163], off
	s_and_b32 s37, 1, s36
	s_cselect_b32 s26, 0, 0x5800
	s_add_i32 s45, s26, 0
	v_add3_u32 v185, s45, v168, v169
	ds_read_b128 v[34:37], v185
	ds_read_b128 v[38:41], v185 offset:6656
	ds_read_b128 v[66:69], v185 offset:32
	ds_read_b128 v[70:73], v185 offset:6688
	s_waitcnt lgkmcnt(3)
	v_mfma_f32_32x32x16_bf16 v[50:65], v[34:37], v[118:121], 0
	ds_read_b128 v[74:77], v185 offset:64
	s_waitcnt lgkmcnt(3)
	v_mfma_f32_32x32x16_bf16 v[34:49], v[38:41], v[118:121], 0
	ds_read_b128 v[82:85], v185 offset:6720
	s_waitcnt lgkmcnt(3)
	v_mfma_f32_32x32x16_bf16 v[50:65], v[66:69], v[114:117], v[50:65]
	ds_read_b128 v[78:81], v185 offset:96
	s_waitcnt lgkmcnt(3)
	v_mfma_f32_32x32x16_bf16 v[34:49], v[70:73], v[114:117], v[34:49]
	ds_read_b128 v[86:89], v185 offset:6752
	s_waitcnt lgkmcnt(3)
	v_mfma_f32_32x32x16_bf16 v[50:65], v[74:77], v[110:113], v[50:65]
	ds_read_b128 v[90:93], v185 offset:128
	s_waitcnt lgkmcnt(3)
	v_mfma_f32_32x32x16_bf16 v[34:49], v[82:85], v[110:113], v[34:49]
	ds_read_b128 v[174:177], v185 offset:6784
	s_waitcnt lgkmcnt(3)
	v_mfma_f32_32x32x16_bf16 v[50:65], v[78:81], v[106:109], v[50:65]
	ds_read_b128 v[94:97], v185 offset:160
	s_waitcnt lgkmcnt(3)
	v_mfma_f32_32x32x16_bf16 v[34:49], v[86:89], v[106:109], v[34:49]
	ds_read_b128 v[182:185], v185 offset:6816
	s_waitcnt lgkmcnt(3)
	v_mfma_f32_32x32x16_bf16 v[50:65], v[90:93], v[102:105], v[50:65]
	s_waitcnt lgkmcnt(2)
	v_mfma_f32_32x32x16_bf16 v[34:49], v[174:177], v[102:105], v[34:49]
	s_waitcnt lgkmcnt(1)
	v_mfma_f32_32x32x16_bf16 v[50:65], v[94:97], v[98:101], v[50:65]
	s_waitcnt lgkmcnt(0)
	v_mfma_f32_32x32x16_bf16 v[34:49], v[182:185], v[98:101], v[34:49]
	v_max3_f32 v66, v50, v51, v52
	s_nop 0
	v_max3_f32 v66, v66, v53, v54
	s_nop 0
	v_max3_f32 v66, v66, v55, v56
	s_nop 0
	v_max3_f32 v66, v66, v57, v58
	s_nop 0
	v_max3_f32 v66, v66, v59, v60
	s_nop 0
	v_max3_f32 v66, v66, v61, v62
	s_nop 0
	v_max3_f32 v66, v66, v63, v64
	s_nop 0
	v_max3_f32 v66, v66, v65, v34
	s_nop 0
	v_max3_f32 v66, v66, v35, v36
	s_nop 0
	v_max3_f32 v66, v66, v37, v38
	s_nop 0
	v_max3_f32 v66, v66, v39, v40
	s_nop 0
	v_max3_f32 v66, v66, v41, v42
	s_nop 0
	v_max3_f32 v66, v66, v43, v44
	s_nop 0
	v_max3_f32 v66, v66, v45, v46
	s_nop 0
	v_max3_f32 v66, v66, v47, v48
	s_nop 0
	v_max3_f32 v66, v66, v49, v49
	v_mov_b32_e32 v67, v66
	s_nop 1
	v_permlane32_swap_b32_e32 v67, v66
	v_max_f32_e32 v66, v66, v67
	s_nop 0
	v_sub_f32_e32 v66, v66, v157
	v_cmp_lt_f32_e32 vcc, s87, v66
	s_cbranch_vccz .LBB0_731
	v_max_f32_e32 v66, v66, v66
	v_max_f32_e32 v67, 0, v66
	v_exp_f32_e64 v66, -v67
	v_add_f32_e32 v157, v157, v67
	v_pk_mul_f32 v[16:17], v[16:17], v[66:67] op_sel_hi:[1,0]
	v_pk_mul_f32 v[14:15], v[14:15], v[66:67] op_sel_hi:[1,0]
	v_pk_mul_f32 v[12:13], v[12:13], v[66:67] op_sel_hi:[1,0]
	v_pk_mul_f32 v[10:11], v[10:11], v[66:67] op_sel_hi:[1,0]
	v_pk_mul_f32 v[8:9], v[8:9], v[66:67] op_sel_hi:[1,0]
	v_pk_mul_f32 v[6:7], v[6:7], v[66:67] op_sel_hi:[1,0]
	v_pk_mul_f32 v[4:5], v[4:5], v[66:67] op_sel_hi:[1,0]
	v_pk_mul_f32 v[2:3], v[2:3], v[66:67] op_sel_hi:[1,0]
	v_pk_mul_f32 v[32:33], v[32:33], v[66:67] op_sel_hi:[1,0]
	v_pk_mul_f32 v[30:31], v[30:31], v[66:67] op_sel_hi:[1,0]
	v_pk_mul_f32 v[28:29], v[28:29], v[66:67] op_sel_hi:[1,0]
	v_pk_mul_f32 v[26:27], v[26:27], v[66:67] op_sel_hi:[1,0]
	v_pk_mul_f32 v[24:25], v[24:25], v[66:67] op_sel_hi:[1,0]
	v_pk_mul_f32 v[22:23], v[22:23], v[66:67] op_sel_hi:[1,0]
	v_pk_mul_f32 v[20:21], v[20:21], v[66:67] op_sel_hi:[1,0]
	v_pk_mul_f32 v[18:19], v[18:19], v[66:67] op_sel_hi:[1,0]
	v_mul_f32_e32 v153, v153, v66
